# barrier: acquire inv issued after the arrival atomic returns (waiters before first poll, XCD-last after its TOP add) so the leader wbl2 is not queued behind it
# speedup vs baseline: 1.0103x; 1.0103x over previous
; __device__ __forceinline__ unsigned xb_ld(unsigned* p)              { return __hip_atomic_load(p, __ATOMIC_RELAXED, __HIP_MEMORY_SCOPE_AGENT); }
; __device__ __forceinline__ unsigned xb_add(unsigned* p, unsigned v) { return __hip_atomic_fetch_add(p, v, __ATOMIC_RELAXED, __HIP_MEMORY_SCOPE_AGENT); }
; #define XB_SPIN(cond, bar) do { unsigned _sp = 0; while (cond) { __builtin_amdgcn_s_sleep(1); \
;     if ((++_sp & 255u) == 0u) { if (xb_ld(&(bar)[XB_TMO])) break; if (_sp > XB_SPIN_CAP) { atomicAdd(&(bar)[XB_TMO], 1u); break; } } } } while (0)
; __device__ __forceinline__ void xcd_barrier(const XcdBarrier& b, int wv) {
;     ...
;         const unsigned old = xb_add(&bar[XB_XSUB(bx)], 1u);
;         const unsigned gen = old / nloc;
;         if (old + 1u == (gen + 1u) * nloc) {
;             __builtin_amdgcn_fence(__ATOMIC_RELEASE, "agent");
;             asm volatile("s_waitcnt vmcnt(0)" ::: "memory");
;             const unsigned og = xb_add(&bar[XB_TOP], 1u);
;             const unsigned tg = og / nx;
;             if (og + 1u == (tg + 1u) * nx) xb_add(&bar[XB_TOPGEN], 1u);
;             else XB_SPIN(xb_ld(&bar[XB_TOPGEN]) == tg, bar);
;             __builtin_amdgcn_fence(__ATOMIC_ACQUIRE, "agent");
;             xb_add(&bar[XB_XGEN(bx)], 1u);
;             asm volatile("s_waitcnt vmcnt(0)" ::: "memory");
;         } else {
;             XB_SPIN(xb_ld(&bar[XB_XGEN(bx)]) == gen, bar);
;             __builtin_amdgcn_fence(__ATOMIC_ACQUIRE, "agent");
;             asm volatile("s_waitcnt vmcnt(0)" ::: "memory");
.LBB0_142:
	s_or_b64 exec, exec, s[6:7]
	v_cvt_f32_u32_e32 v4, v2
	s_waitcnt vmcnt(0)
	v_readfirstlane_b32 s4, v3
	v_sub_u32_e32 v3, 0, v2
	v_rcp_iflag_f32_e32 v4, v4
	v_add_u32_e32 v5, s4, v1
	v_mul_f32_e32 v4, 0x4f7ffffe, v4
	v_cvt_u32_f32_e32 v4, v4
	v_mul_lo_u32 v1, v3, v4
	v_mul_hi_u32 v1, v4, v1
	v_add_u32_e32 v1, v4, v1
	v_mul_hi_u32 v1, v5, v1
	v_mul_lo_u32 v3, v1, v2
	v_sub_u32_e32 v3, v5, v3
	v_add_u32_e32 v4, 1, v1
	v_cmp_ge_u32_e32 vcc, v3, v2
	s_nop 1
	v_cndmask_b32_e32 v1, v1, v4, vcc
	v_sub_u32_e32 v4, v3, v2
	v_cndmask_b32_e32 v3, v3, v4, vcc
	v_add_u32_e32 v4, 1, v1
	v_cmp_ge_u32_e32 vcc, v3, v2
	v_add_u32_e32 v3, 1, v5
	s_nop 0
	v_cndmask_b32_e32 v1, v1, v4, vcc
	v_mul_lo_u32 v4, v2, v1
	v_add_u32_e32 v2, v4, v2
	v_cmp_ne_u32_e32 vcc, v3, v2
	s_and_saveexec_b64 s[4:5], vcc
	s_xor_b64 s[4:5], exec, s[4:5]
	s_cbranch_execz .LBB0_156
	s_movk_i32 s6, 0xd00
	buffer_inv sc1
	v_mad_u32_u24 v2, v1, v0, v0
	s_nop 0
	v_readfirstlane_b32 s98, v2
	s_mov_b32 s7, 0
	s_lshl_b64 s[6:7], s[6:7], 2
	s_add_u32 s10, s82, s6
	s_addc_u32 s11, s83, s7
	s_waitcnt lgkmcnt(0)
	v_mov_b32_e32 v0, 0
	global_load_dword v2, v0, s[10:11] sc1
	s_waitcnt vmcnt(0)
	v_cmp_gt_u32_e32 vcc, s98, v2
	s_and_saveexec_b64 s[6:7], vcc
	s_cbranch_execz .LBB0_155
	s_add_u32 s8, s30, 0x3e9200
	s_addc_u32 s9, s31, 0
	s_mov_b32 s36, 1
	s_mov_b64 s[12:13], 0
	s_branch .LBB0_146

; __device__ __forceinline__ unsigned xb_ld(unsigned* p)              { return __hip_atomic_load(p, __ATOMIC_RELAXED, __HIP_MEMORY_SCOPE_AGENT); }
; __device__ __forceinline__ unsigned xb_add(unsigned* p, unsigned v) { return __hip_atomic_fetch_add(p, v, __ATOMIC_RELAXED, __HIP_MEMORY_SCOPE_AGENT); }
; #define XB_SPIN(cond, bar) do { unsigned _sp = 0; while (cond) { __builtin_amdgcn_s_sleep(1); \
;     if ((++_sp & 255u) == 0u) { if (xb_ld(&(bar)[XB_TMO])) break; if (_sp > XB_SPIN_CAP) { atomicAdd(&(bar)[XB_TMO], 1u); break; } } } } while (0)
; __device__ __forceinline__ void xcd_barrier(const XcdBarrier& b, int wv) {
;     ...
;             __builtin_amdgcn_fence(__ATOMIC_RELEASE, "agent");
;             asm volatile("s_waitcnt vmcnt(0)" ::: "memory");
;             const unsigned og = xb_add(&bar[XB_TOP], 1u);
;             const unsigned tg = og / nx;
;             if (og + 1u == (tg + 1u) * nx) xb_add(&bar[XB_TOPGEN], 1u);
;             else XB_SPIN(xb_ld(&bar[XB_TOPGEN]) == tg, bar);
;             __builtin_amdgcn_fence(__ATOMIC_ACQUIRE, "agent");
.LBB0_156:
	s_andn2_saveexec_b64 s[4:5], s[4:5]
	s_cbranch_execz .LBB0_176
	s_mov_b64 s[4:5], exec
	buffer_wbl2 sc1
	s_waitcnt lgkmcnt(0)
	s_waitcnt vmcnt(0)
	v_mbcnt_lo_u32_b32 v1, s4, 0
	v_mbcnt_hi_u32_b32 v1, s5, v1
	v_cmp_eq_u32_e32 vcc, 0, v1
	s_and_saveexec_b64 s[6:7], vcc
	s_cbranch_execz .LBB0_159
	s_bcnt1_i32_b64 s4, s[4:5]
	v_mov_b32_e32 v2, 0x3ec000
	v_mov_b32_e32 v3, s4
	global_atomic_add v2, v2, v3, s[30:31] offset:1024 sc0
	buffer_inv sc1

; __device__ __forceinline__ unsigned xb_ld(unsigned* p)              { return __hip_atomic_load(p, __ATOMIC_RELAXED, __HIP_MEMORY_SCOPE_AGENT); }
; __device__ __forceinline__ unsigned xb_add(unsigned* p, unsigned v) { return __hip_atomic_fetch_add(p, v, __ATOMIC_RELAXED, __HIP_MEMORY_SCOPE_AGENT); }
; #define XB_SPIN(cond, bar) do { unsigned _sp = 0; while (cond) { __builtin_amdgcn_s_sleep(1); \
;     if ((++_sp & 255u) == 0u) { if (xb_ld(&(bar)[XB_TMO])) break; if (_sp > XB_SPIN_CAP) { atomicAdd(&(bar)[XB_TMO], 1u); break; } } } } while (0)
; __device__ __forceinline__ void xcd_barrier(const XcdBarrier& b, int wv) {
;     ...
;         const unsigned old = xb_add(&bar[XB_XSUB(bx)], 1u);
;         const unsigned gen = old / nloc;
;         if (old + 1u == (gen + 1u) * nloc) {
;             __builtin_amdgcn_fence(__ATOMIC_RELEASE, "agent");
;             asm volatile("s_waitcnt vmcnt(0)" ::: "memory");
;             const unsigned og = xb_add(&bar[XB_TOP], 1u);
;             const unsigned tg = og / nx;
;             if (og + 1u == (tg + 1u) * nx) xb_add(&bar[XB_TOPGEN], 1u);
;             else XB_SPIN(xb_ld(&bar[XB_TOPGEN]) == tg, bar);
;             __builtin_amdgcn_fence(__ATOMIC_ACQUIRE, "agent");
;             xb_add(&bar[XB_XGEN(bx)], 1u);
;             asm volatile("s_waitcnt vmcnt(0)" ::: "memory");
;         } else {
;             XB_SPIN(xb_ld(&bar[XB_XGEN(bx)]) == gen, bar);
;             __builtin_amdgcn_fence(__ATOMIC_ACQUIRE, "agent");
;             asm volatile("s_waitcnt vmcnt(0)" ::: "memory");
.LBB0_243:
	s_or_b64 exec, exec, s[14:15]
	v_cvt_f32_u32_e32 v5, v3
	s_waitcnt vmcnt(0)
	v_readfirstlane_b32 s10, v4
	v_sub_u32_e32 v4, 0, v3
	v_rcp_iflag_f32_e32 v5, v5
	v_add_u32_e32 v6, s10, v1
	v_mul_f32_e32 v5, 0x4f7ffffe, v5
	v_cvt_u32_f32_e32 v5, v5
	v_mul_lo_u32 v1, v4, v5
	v_mul_hi_u32 v1, v5, v1
	v_add_u32_e32 v1, v5, v1
	v_mul_hi_u32 v1, v6, v1
	v_mul_lo_u32 v4, v1, v3
	v_sub_u32_e32 v4, v6, v4
	v_add_u32_e32 v5, 1, v1
	v_cmp_ge_u32_e32 vcc, v4, v3
	s_nop 1
	v_cndmask_b32_e32 v1, v1, v5, vcc
	v_sub_u32_e32 v5, v4, v3
	v_cndmask_b32_e32 v4, v4, v5, vcc
	v_add_u32_e32 v5, 1, v1
	v_cmp_ge_u32_e32 vcc, v4, v3
	v_add_u32_e32 v4, 1, v6
	s_nop 0
	v_cndmask_b32_e32 v1, v1, v5, vcc
	v_mul_lo_u32 v5, v3, v1
	v_add_u32_e32 v3, v5, v3
	v_cmp_ne_u32_e32 vcc, v4, v3
	s_and_saveexec_b64 s[10:11], vcc
	s_xor_b64 s[10:11], exec, s[10:11]
	s_cbranch_execz .LBB0_257
	s_movk_i32 s36, 0xd00
	buffer_inv sc1
	v_mad_u32_u24 v2, v1, v2, v2
	s_nop 0
	v_readfirstlane_b32 s98, v2
	s_lshl_b64 s[14:15], s[36:37], 2
	s_add_u32 s16, s82, s14
	s_addc_u32 s17, s83, s15
	s_waitcnt lgkmcnt(0)
	global_load_dword v2, v0, s[16:17] sc1
	s_waitcnt vmcnt(0)
	v_cmp_gt_u32_e32 vcc, s98, v2
	s_and_saveexec_b64 s[14:15], vcc
	s_cbranch_execz .LBB0_256
	s_mov_b32 s36, 1
	s_mov_b64 s[20:21], 0
	s_branch .LBB0_247

; __device__ __forceinline__ unsigned xb_ld(unsigned* p)              { return __hip_atomic_load(p, __ATOMIC_RELAXED, __HIP_MEMORY_SCOPE_AGENT); }
; __device__ __forceinline__ unsigned xb_add(unsigned* p, unsigned v) { return __hip_atomic_fetch_add(p, v, __ATOMIC_RELAXED, __HIP_MEMORY_SCOPE_AGENT); }
; #define XB_SPIN(cond, bar) do { unsigned _sp = 0; while (cond) { __builtin_amdgcn_s_sleep(1); \
;     if ((++_sp & 255u) == 0u) { if (xb_ld(&(bar)[XB_TMO])) break; if (_sp > XB_SPIN_CAP) { atomicAdd(&(bar)[XB_TMO], 1u); break; } } } } while (0)
; __device__ __forceinline__ void xcd_barrier(const XcdBarrier& b, int wv) {
;     ...
;             __builtin_amdgcn_fence(__ATOMIC_RELEASE, "agent");
;             asm volatile("s_waitcnt vmcnt(0)" ::: "memory");
;             const unsigned og = xb_add(&bar[XB_TOP], 1u);
;             const unsigned tg = og / nx;
;             if (og + 1u == (tg + 1u) * nx) xb_add(&bar[XB_TOPGEN], 1u);
;             else XB_SPIN(xb_ld(&bar[XB_TOPGEN]) == tg, bar);
;             __builtin_amdgcn_fence(__ATOMIC_ACQUIRE, "agent");
.LBB0_257:
	s_andn2_saveexec_b64 s[10:11], s[10:11]
	s_cbranch_execz .LBB0_277
	s_mov_b64 s[10:11], exec
	buffer_wbl2 sc1
	s_waitcnt lgkmcnt(0)
	s_waitcnt vmcnt(0)
	v_mbcnt_lo_u32_b32 v1, s10, 0
	v_mbcnt_hi_u32_b32 v1, s11, v1
	v_cmp_eq_u32_e32 vcc, 0, v1
	s_and_saveexec_b64 s[14:15], vcc
	s_cbranch_execz .LBB0_260
	s_bcnt1_i32_b64 s10, s[10:11]
	v_mov_b32_e32 v3, s10
	v_readlane_b32 s10, v254, 3
	v_readlane_b32 s11, v254, 4
	s_nop 4
	global_atomic_add v3, v0, v3, s[10:11] sc0
	buffer_inv sc1

; __device__ __forceinline__ unsigned xb_ld(unsigned* p)              { return __hip_atomic_load(p, __ATOMIC_RELAXED, __HIP_MEMORY_SCOPE_AGENT); }
; __device__ __forceinline__ unsigned xb_add(unsigned* p, unsigned v) { return __hip_atomic_fetch_add(p, v, __ATOMIC_RELAXED, __HIP_MEMORY_SCOPE_AGENT); }
; #define XB_SPIN(cond, bar) do { unsigned _sp = 0; while (cond) { __builtin_amdgcn_s_sleep(1); \
;     if ((++_sp & 255u) == 0u) { if (xb_ld(&(bar)[XB_TMO])) break; if (_sp > XB_SPIN_CAP) { atomicAdd(&(bar)[XB_TMO], 1u); break; } } } } while (0)
; __device__ __forceinline__ void xcd_barrier(const XcdBarrier& b, int wv) {
;     ...
;         const unsigned old = xb_add(&bar[XB_XSUB(bx)], 1u);
;         const unsigned gen = old / nloc;
;         if (old + 1u == (gen + 1u) * nloc) {
;             __builtin_amdgcn_fence(__ATOMIC_RELEASE, "agent");
;             asm volatile("s_waitcnt vmcnt(0)" ::: "memory");
;             const unsigned og = xb_add(&bar[XB_TOP], 1u);
;             const unsigned tg = og / nx;
;             if (og + 1u == (tg + 1u) * nx) xb_add(&bar[XB_TOPGEN], 1u);
;             else XB_SPIN(xb_ld(&bar[XB_TOPGEN]) == tg, bar);
;             __builtin_amdgcn_fence(__ATOMIC_ACQUIRE, "agent");
;             xb_add(&bar[XB_XGEN(bx)], 1u);
;             asm volatile("s_waitcnt vmcnt(0)" ::: "memory");
;         } else {
;             XB_SPIN(xb_ld(&bar[XB_XGEN(bx)]) == gen, bar);
;             __builtin_amdgcn_fence(__ATOMIC_ACQUIRE, "agent");
;             asm volatile("s_waitcnt vmcnt(0)" ::: "memory");
.LBB0_351:
	s_or_b64 exec, exec, s[10:11]
	v_cvt_f32_u32_e32 v5, v3
	s_waitcnt vmcnt(0)
	v_readfirstlane_b32 s6, v4
	v_sub_u32_e32 v4, 0, v3
	v_rcp_iflag_f32_e32 v5, v5
	v_add_u32_e32 v6, s6, v1
	v_mul_f32_e32 v5, 0x4f7ffffe, v5
	v_cvt_u32_f32_e32 v5, v5
	v_mul_lo_u32 v1, v4, v5
	v_mul_hi_u32 v1, v5, v1
	v_add_u32_e32 v1, v5, v1
	v_mul_hi_u32 v1, v6, v1
	v_mul_lo_u32 v4, v1, v3
	v_sub_u32_e32 v4, v6, v4
	v_add_u32_e32 v5, 1, v1
	v_cmp_ge_u32_e32 vcc, v4, v3
	s_nop 1
	v_cndmask_b32_e32 v1, v1, v5, vcc
	v_sub_u32_e32 v5, v4, v3
	v_cndmask_b32_e32 v4, v4, v5, vcc
	v_add_u32_e32 v5, 1, v1
	v_cmp_ge_u32_e32 vcc, v4, v3
	v_add_u32_e32 v4, 1, v6
	s_nop 0
	v_cndmask_b32_e32 v1, v1, v5, vcc
	v_mul_lo_u32 v5, v3, v1
	v_add_u32_e32 v3, v5, v3
	v_cmp_ne_u32_e32 vcc, v4, v3
	s_and_saveexec_b64 s[6:7], vcc
	s_xor_b64 s[6:7], exec, s[6:7]
	s_cbranch_execz .LBB0_365
	s_movk_i32 s36, 0xd00
	buffer_inv sc1
	v_mad_u32_u24 v2, v1, v2, v2
	s_nop 0
	v_readfirstlane_b32 s98, v2
	s_lshl_b64 s[10:11], s[36:37], 2
	s_add_u32 s14, s82, s10
	s_addc_u32 s15, s83, s11
	s_waitcnt lgkmcnt(0)
	global_load_dword v2, v0, s[14:15] sc1
	s_waitcnt vmcnt(0)
	v_cmp_gt_u32_e32 vcc, s98, v2
	s_and_saveexec_b64 s[10:11], vcc
	s_cbranch_execz .LBB0_364
	s_mov_b32 s36, 1
	s_mov_b64 s[16:17], 0
	s_branch .LBB0_355

; __device__ __forceinline__ unsigned xb_ld(unsigned* p)              { return __hip_atomic_load(p, __ATOMIC_RELAXED, __HIP_MEMORY_SCOPE_AGENT); }
; __device__ __forceinline__ unsigned xb_add(unsigned* p, unsigned v) { return __hip_atomic_fetch_add(p, v, __ATOMIC_RELAXED, __HIP_MEMORY_SCOPE_AGENT); }
; #define XB_SPIN(cond, bar) do { unsigned _sp = 0; while (cond) { __builtin_amdgcn_s_sleep(1); \
;     if ((++_sp & 255u) == 0u) { if (xb_ld(&(bar)[XB_TMO])) break; if (_sp > XB_SPIN_CAP) { atomicAdd(&(bar)[XB_TMO], 1u); break; } } } } while (0)
; __device__ __forceinline__ void xcd_barrier(const XcdBarrier& b, int wv) {
;     ...
;             __builtin_amdgcn_fence(__ATOMIC_RELEASE, "agent");
;             asm volatile("s_waitcnt vmcnt(0)" ::: "memory");
;             const unsigned og = xb_add(&bar[XB_TOP], 1u);
;             const unsigned tg = og / nx;
;             if (og + 1u == (tg + 1u) * nx) xb_add(&bar[XB_TOPGEN], 1u);
;             else XB_SPIN(xb_ld(&bar[XB_TOPGEN]) == tg, bar);
;             __builtin_amdgcn_fence(__ATOMIC_ACQUIRE, "agent");
.LBB0_365:
	s_andn2_saveexec_b64 s[6:7], s[6:7]
	s_cbranch_execz .LBB0_385
	s_mov_b64 s[6:7], exec
	buffer_wbl2 sc1
	s_waitcnt lgkmcnt(0)
	s_waitcnt vmcnt(0)
	v_mbcnt_lo_u32_b32 v1, s6, 0
	v_mbcnt_hi_u32_b32 v1, s7, v1
	v_cmp_eq_u32_e32 vcc, 0, v1
	s_and_saveexec_b64 s[10:11], vcc
	s_cbranch_execz .LBB0_368
	s_bcnt1_i32_b64 s6, s[6:7]
	v_mov_b32_e32 v3, s6
	v_readlane_b32 s6, v254, 3
	v_readlane_b32 s7, v254, 4
	s_nop 4
	global_atomic_add v3, v0, v3, s[6:7] sc0
	buffer_inv sc1

; __device__ __forceinline__ unsigned xb_ld(unsigned* p)              { return __hip_atomic_load(p, __ATOMIC_RELAXED, __HIP_MEMORY_SCOPE_AGENT); }
; __device__ __forceinline__ unsigned xb_add(unsigned* p, unsigned v) { return __hip_atomic_fetch_add(p, v, __ATOMIC_RELAXED, __HIP_MEMORY_SCOPE_AGENT); }
; #define XB_SPIN(cond, bar) do { unsigned _sp = 0; while (cond) { __builtin_amdgcn_s_sleep(1); \
;     if ((++_sp & 255u) == 0u) { if (xb_ld(&(bar)[XB_TMO])) break; if (_sp > XB_SPIN_CAP) { atomicAdd(&(bar)[XB_TMO], 1u); break; } } } } while (0)
; __device__ __forceinline__ void xcd_barrier(const XcdBarrier& b, int wv) {
;     ...
;         const unsigned old = xb_add(&bar[XB_XSUB(bx)], 1u);
;         const unsigned gen = old / nloc;
;         if (old + 1u == (gen + 1u) * nloc) {
;             __builtin_amdgcn_fence(__ATOMIC_RELEASE, "agent");
;             asm volatile("s_waitcnt vmcnt(0)" ::: "memory");
;             const unsigned og = xb_add(&bar[XB_TOP], 1u);
;             const unsigned tg = og / nx;
;             if (og + 1u == (tg + 1u) * nx) xb_add(&bar[XB_TOPGEN], 1u);
;             else XB_SPIN(xb_ld(&bar[XB_TOPGEN]) == tg, bar);
;             __builtin_amdgcn_fence(__ATOMIC_ACQUIRE, "agent");
;             xb_add(&bar[XB_XGEN(bx)], 1u);
;             asm volatile("s_waitcnt vmcnt(0)" ::: "memory");
;         } else {
;             XB_SPIN(xb_ld(&bar[XB_XGEN(bx)]) == gen, bar);
;             __builtin_amdgcn_fence(__ATOMIC_ACQUIRE, "agent");
;             asm volatile("s_waitcnt vmcnt(0)" ::: "memory");
.LBB0_525:
	s_or_b64 exec, exec, s[6:7]
	v_cvt_f32_u32_e32 v5, v3
	s_waitcnt vmcnt(0)
	v_readfirstlane_b32 s4, v4
	v_sub_u32_e32 v4, 0, v3
	v_rcp_iflag_f32_e32 v5, v5
	v_add_u32_e32 v6, s4, v1
	v_mul_f32_e32 v5, 0x4f7ffffe, v5
	v_cvt_u32_f32_e32 v5, v5
	v_mul_lo_u32 v1, v4, v5
	v_mul_hi_u32 v1, v5, v1
	v_add_u32_e32 v1, v5, v1
	v_mul_hi_u32 v1, v6, v1
	v_mul_lo_u32 v4, v1, v3
	v_sub_u32_e32 v4, v6, v4
	v_add_u32_e32 v5, 1, v1
	v_cmp_ge_u32_e32 vcc, v4, v3
	s_nop 1
	v_cndmask_b32_e32 v1, v1, v5, vcc
	v_sub_u32_e32 v5, v4, v3
	v_cndmask_b32_e32 v4, v4, v5, vcc
	v_add_u32_e32 v5, 1, v1
	v_cmp_ge_u32_e32 vcc, v4, v3
	v_add_u32_e32 v4, 1, v6
	s_nop 0
	v_cndmask_b32_e32 v1, v1, v5, vcc
	v_mul_lo_u32 v5, v3, v1
	v_add_u32_e32 v3, v5, v3
	v_cmp_ne_u32_e32 vcc, v4, v3
	s_and_saveexec_b64 s[4:5], vcc
	s_xor_b64 s[4:5], exec, s[4:5]
	s_cbranch_execz .LBB0_539
	s_movk_i32 s36, 0xd00
	buffer_inv sc1
	v_mad_u32_u24 v2, v1, v2, v2
	s_nop 0
	v_readfirstlane_b32 s98, v2
	s_lshl_b64 s[6:7], s[36:37], 2
	s_add_u32 s8, s82, s6
	s_addc_u32 s9, s83, s7
	s_waitcnt lgkmcnt(0)
	global_load_dword v2, v0, s[8:9] sc1
	s_waitcnt vmcnt(0)
	v_cmp_gt_u32_e32 vcc, s98, v2
	s_and_saveexec_b64 s[6:7], vcc
	s_cbranch_execz .LBB0_538
	s_mov_b32 s36, 1
	s_mov_b64 s[10:11], 0
	s_branch .LBB0_529

; __device__ __forceinline__ unsigned xb_ld(unsigned* p)              { return __hip_atomic_load(p, __ATOMIC_RELAXED, __HIP_MEMORY_SCOPE_AGENT); }
; __device__ __forceinline__ unsigned xb_add(unsigned* p, unsigned v) { return __hip_atomic_fetch_add(p, v, __ATOMIC_RELAXED, __HIP_MEMORY_SCOPE_AGENT); }
; #define XB_SPIN(cond, bar) do { unsigned _sp = 0; while (cond) { __builtin_amdgcn_s_sleep(1); \
;     if ((++_sp & 255u) == 0u) { if (xb_ld(&(bar)[XB_TMO])) break; if (_sp > XB_SPIN_CAP) { atomicAdd(&(bar)[XB_TMO], 1u); break; } } } } while (0)
; __device__ __forceinline__ void xcd_barrier(const XcdBarrier& b, int wv) {
;     ...
;             __builtin_amdgcn_fence(__ATOMIC_RELEASE, "agent");
;             asm volatile("s_waitcnt vmcnt(0)" ::: "memory");
;             const unsigned og = xb_add(&bar[XB_TOP], 1u);
;             const unsigned tg = og / nx;
;             if (og + 1u == (tg + 1u) * nx) xb_add(&bar[XB_TOPGEN], 1u);
;             else XB_SPIN(xb_ld(&bar[XB_TOPGEN]) == tg, bar);
;             __builtin_amdgcn_fence(__ATOMIC_ACQUIRE, "agent");
.LBB0_539:
	s_andn2_saveexec_b64 s[4:5], s[4:5]
	s_cbranch_execz .LBB0_559
	s_mov_b64 s[4:5], exec
	buffer_wbl2 sc1
	s_waitcnt lgkmcnt(0)
	s_waitcnt vmcnt(0)
	v_mbcnt_lo_u32_b32 v1, s4, 0
	v_mbcnt_hi_u32_b32 v1, s5, v1
	v_cmp_eq_u32_e32 vcc, 0, v1
	s_and_saveexec_b64 s[6:7], vcc
	s_cbranch_execz .LBB0_542
	s_bcnt1_i32_b64 s4, s[4:5]
	v_mov_b32_e32 v3, s4
	v_readlane_b32 s4, v254, 3
	v_readlane_b32 s5, v254, 4
	s_nop 4
	global_atomic_add v3, v0, v3, s[4:5] sc0
	buffer_inv sc1

; __device__ __forceinline__ unsigned xb_ld(unsigned* p)              { return __hip_atomic_load(p, __ATOMIC_RELAXED, __HIP_MEMORY_SCOPE_AGENT); }
; __device__ __forceinline__ unsigned xb_add(unsigned* p, unsigned v) { return __hip_atomic_fetch_add(p, v, __ATOMIC_RELAXED, __HIP_MEMORY_SCOPE_AGENT); }
; #define XB_SPIN(cond, bar) do { unsigned _sp = 0; while (cond) { __builtin_amdgcn_s_sleep(1); \
;     if ((++_sp & 255u) == 0u) { if (xb_ld(&(bar)[XB_TMO])) break; if (_sp > XB_SPIN_CAP) { atomicAdd(&(bar)[XB_TMO], 1u); break; } } } } while (0)
; __device__ __forceinline__ void xcd_barrier(const XcdBarrier& b, int wv) {
;     ...
;         const unsigned old = xb_add(&bar[XB_XSUB(bx)], 1u);
;         const unsigned gen = old / nloc;
;         if (old + 1u == (gen + 1u) * nloc) {
;             __builtin_amdgcn_fence(__ATOMIC_RELEASE, "agent");
;             asm volatile("s_waitcnt vmcnt(0)" ::: "memory");
;             const unsigned og = xb_add(&bar[XB_TOP], 1u);
;             const unsigned tg = og / nx;
;             if (og + 1u == (tg + 1u) * nx) xb_add(&bar[XB_TOPGEN], 1u);
;             else XB_SPIN(xb_ld(&bar[XB_TOPGEN]) == tg, bar);
;             __builtin_amdgcn_fence(__ATOMIC_ACQUIRE, "agent");
;             xb_add(&bar[XB_XGEN(bx)], 1u);
;             asm volatile("s_waitcnt vmcnt(0)" ::: "memory");
;         } else {
;             XB_SPIN(xb_ld(&bar[XB_XGEN(bx)]) == gen, bar);
;             __builtin_amdgcn_fence(__ATOMIC_ACQUIRE, "agent");
;             asm volatile("s_waitcnt vmcnt(0)" ::: "memory");
.LBB0_764:
	s_or_b64 exec, exec, s[6:7]
	v_cvt_f32_u32_e32 v5, v3
	s_waitcnt vmcnt(0)
	v_readfirstlane_b32 s4, v4
	v_sub_u32_e32 v4, 0, v3
	v_rcp_iflag_f32_e32 v5, v5
	v_add_u32_e32 v6, s4, v1
	v_mul_f32_e32 v5, 0x4f7ffffe, v5
	v_cvt_u32_f32_e32 v5, v5
	v_mul_lo_u32 v1, v4, v5
	v_mul_hi_u32 v1, v5, v1
	v_add_u32_e32 v1, v5, v1
	v_mul_hi_u32 v1, v6, v1
	v_mul_lo_u32 v4, v1, v3
	v_sub_u32_e32 v4, v6, v4
	v_add_u32_e32 v5, 1, v1
	v_cmp_ge_u32_e32 vcc, v4, v3
	s_nop 1
	v_cndmask_b32_e32 v1, v1, v5, vcc
	v_sub_u32_e32 v5, v4, v3
	v_cndmask_b32_e32 v4, v4, v5, vcc
	v_add_u32_e32 v5, 1, v1
	v_cmp_ge_u32_e32 vcc, v4, v3
	v_add_u32_e32 v4, 1, v6
	s_nop 0
	v_cndmask_b32_e32 v1, v1, v5, vcc
	v_mul_lo_u32 v5, v3, v1
	v_add_u32_e32 v3, v5, v3
	v_cmp_ne_u32_e32 vcc, v4, v3
	s_and_saveexec_b64 s[4:5], vcc
	s_xor_b64 s[4:5], exec, s[4:5]
	s_cbranch_execz .LBB0_778
	s_movk_i32 s36, 0xd00
	buffer_inv sc1
	v_mad_u32_u24 v2, v1, v2, v2
	s_nop 0
	v_readfirstlane_b32 s98, v2
	s_lshl_b64 s[6:7], s[36:37], 2
	s_add_u32 s8, s82, s6
	s_addc_u32 s9, s83, s7
	s_waitcnt lgkmcnt(0)
	global_load_dword v2, v0, s[8:9] sc1
	s_waitcnt vmcnt(0)
	v_cmp_gt_u32_e32 vcc, s98, v2
	s_and_saveexec_b64 s[6:7], vcc
	s_cbranch_execz .LBB0_777
	s_mov_b32 s36, 1
	s_mov_b64 s[12:13], 0
	s_branch .LBB0_768

; __device__ __forceinline__ unsigned xb_ld(unsigned* p)              { return __hip_atomic_load(p, __ATOMIC_RELAXED, __HIP_MEMORY_SCOPE_AGENT); }
; __device__ __forceinline__ unsigned xb_add(unsigned* p, unsigned v) { return __hip_atomic_fetch_add(p, v, __ATOMIC_RELAXED, __HIP_MEMORY_SCOPE_AGENT); }
; #define XB_SPIN(cond, bar) do { unsigned _sp = 0; while (cond) { __builtin_amdgcn_s_sleep(1); \
;     if ((++_sp & 255u) == 0u) { if (xb_ld(&(bar)[XB_TMO])) break; if (_sp > XB_SPIN_CAP) { atomicAdd(&(bar)[XB_TMO], 1u); break; } } } } while (0)
; __device__ __forceinline__ void xcd_barrier(const XcdBarrier& b, int wv) {
;     ...
;         const unsigned old = xb_add(&bar[XB_XSUB(bx)], 1u);
;         const unsigned gen = old / nloc;
;         if (old + 1u == (gen + 1u) * nloc) {
;             __builtin_amdgcn_fence(__ATOMIC_RELEASE, "agent");
;             asm volatile("s_waitcnt vmcnt(0)" ::: "memory");
;             const unsigned og = xb_add(&bar[XB_TOP], 1u);
;             const unsigned tg = og / nx;
;             if (og + 1u == (tg + 1u) * nx) xb_add(&bar[XB_TOPGEN], 1u);
;             else XB_SPIN(xb_ld(&bar[XB_TOPGEN]) == tg, bar);
;             __builtin_amdgcn_fence(__ATOMIC_ACQUIRE, "agent");
;             xb_add(&bar[XB_XGEN(bx)], 1u);
;             asm volatile("s_waitcnt vmcnt(0)" ::: "memory");
;         } else {
;             XB_SPIN(xb_ld(&bar[XB_XGEN(bx)]) == gen, bar);
;             __builtin_amdgcn_fence(__ATOMIC_ACQUIRE, "agent");
;             asm volatile("s_waitcnt vmcnt(0)" ::: "memory");
.LBB0_818:
	s_or_b64 exec, exec, s[10:11]
	v_cvt_f32_u32_e32 v8, v6
	s_waitcnt vmcnt(0)
	v_readfirstlane_b32 s8, v7
	v_sub_u32_e32 v7, 0, v6
	v_rcp_iflag_f32_e32 v8, v8
	v_add_u32_e32 v9, s8, v5
	v_mul_f32_e32 v8, 0x4f7ffffe, v8
	v_cvt_u32_f32_e32 v8, v8
	v_mul_lo_u32 v5, v7, v8
	v_mul_hi_u32 v5, v8, v5
	v_add_u32_e32 v5, v8, v5
	v_mul_hi_u32 v5, v9, v5
	v_mul_lo_u32 v7, v5, v6
	v_sub_u32_e32 v7, v9, v7
	v_add_u32_e32 v8, 1, v5
	v_cmp_ge_u32_e32 vcc, v7, v6
	s_nop 1
	v_cndmask_b32_e32 v5, v5, v8, vcc
	v_sub_u32_e32 v8, v7, v6
	v_cndmask_b32_e32 v7, v7, v8, vcc
	v_add_u32_e32 v8, 1, v5
	v_cmp_ge_u32_e32 vcc, v7, v6
	v_add_u32_e32 v7, 1, v9
	s_nop 0
	v_cndmask_b32_e32 v5, v5, v8, vcc
	v_mul_lo_u32 v8, v6, v5
	v_add_u32_e32 v6, v8, v6
	v_cmp_ne_u32_e32 vcc, v7, v6
	s_and_saveexec_b64 s[8:9], vcc
	s_xor_b64 s[8:9], exec, s[8:9]
	s_cbranch_execz .LBB0_832
	s_movk_i32 s10, 0xd00
	buffer_inv sc1
	v_mad_u32_u24 v6, v5, v4, v4
	s_nop 0
	v_readfirstlane_b32 s98, v6
	s_mov_b32 s11, 0
	s_lshl_b64 s[10:11], s[10:11], 2
	s_add_u32 s12, s82, s10
	s_addc_u32 s13, s83, s11
	s_waitcnt lgkmcnt(0)
	v_mov_b32_e32 v4, 0
	global_load_dword v6, v4, s[12:13] sc1
	s_waitcnt vmcnt(0)
	v_cmp_gt_u32_e32 vcc, s98, v6
	s_and_saveexec_b64 s[10:11], vcc
	s_cbranch_execz .LBB0_831
	s_mov_b32 s25, 1
	s_mov_b64 s[14:15], 0
	s_branch .LBB0_822

; __device__ __forceinline__ unsigned xb_ld(unsigned* p)              { return __hip_atomic_load(p, __ATOMIC_RELAXED, __HIP_MEMORY_SCOPE_AGENT); }
; __device__ __forceinline__ unsigned xb_add(unsigned* p, unsigned v) { return __hip_atomic_fetch_add(p, v, __ATOMIC_RELAXED, __HIP_MEMORY_SCOPE_AGENT); }
; #define XB_SPIN(cond, bar) do { unsigned _sp = 0; while (cond) { __builtin_amdgcn_s_sleep(1); \
;     if ((++_sp & 255u) == 0u) { if (xb_ld(&(bar)[XB_TMO])) break; if (_sp > XB_SPIN_CAP) { atomicAdd(&(bar)[XB_TMO], 1u); break; } } } } while (0)
; __device__ __forceinline__ void xcd_barrier(const XcdBarrier& b, int wv) {
;     ...
;             __builtin_amdgcn_fence(__ATOMIC_RELEASE, "agent");
;             asm volatile("s_waitcnt vmcnt(0)" ::: "memory");
;             const unsigned og = xb_add(&bar[XB_TOP], 1u);
;             const unsigned tg = og / nx;
;             if (og + 1u == (tg + 1u) * nx) xb_add(&bar[XB_TOPGEN], 1u);
;             else XB_SPIN(xb_ld(&bar[XB_TOPGEN]) == tg, bar);
;             __builtin_amdgcn_fence(__ATOMIC_ACQUIRE, "agent");
.LBB0_832:
	s_andn2_saveexec_b64 s[8:9], s[8:9]
	s_cbranch_execz .LBB0_852
	s_mov_b64 s[8:9], exec
	buffer_wbl2 sc1
	s_waitcnt lgkmcnt(0)
	s_waitcnt vmcnt(0)
	v_mbcnt_lo_u32_b32 v5, s8, 0
	v_mbcnt_hi_u32_b32 v5, s9, v5
	v_cmp_eq_u32_e32 vcc, 0, v5
	s_and_saveexec_b64 s[10:11], vcc
	s_cbranch_execz .LBB0_835
	s_bcnt1_i32_b64 s8, s[8:9]
	v_mov_b32_e32 v7, s8
	v_readlane_b32 s8, v254, 3
	v_mov_b32_e32 v6, 0
	v_readlane_b32 s9, v254, 4
	s_nop 4
	global_atomic_add v6, v6, v7, s[8:9] sc0
	buffer_inv sc1
